# grid barrier release: non-leader workgroups poll the cross-XCD generation directly (one hop less)
# baseline (speedup 1.0000x reference)
; __device__ __forceinline__ unsigned xb_ld(unsigned* p)              { return __hip_atomic_load(p, __ATOMIC_RELAXED, __HIP_MEMORY_SCOPE_AGENT); }
; __device__ __forceinline__ unsigned xb_add(unsigned* p, unsigned v) { return __hip_atomic_fetch_add(p, v, __ATOMIC_RELAXED, __HIP_MEMORY_SCOPE_AGENT); }
; #define XB_SPIN(cond, bar) do { unsigned _sp = 0; while (cond) { __builtin_amdgcn_s_sleep(1); \
;     if ((++_sp & 255u) == 0u) { if (xb_ld(&(bar)[XB_TMO])) break; if (_sp > XB_SPIN_CAP) { atomicAdd(&(bar)[XB_TMO], 1u); break; } } } } while (0)
; __device__ __forceinline__ void xcd_barrier(const XcdBarrier& b) {
;     ...
;     if (threadIdx.x == 0) {
;         unsigned* bar = b.bar;
;         __builtin_amdgcn_s_waitcnt(0);
;         unsigned nloc = b.st[0], nx = b.st[1];
;         if (nloc == 0u) { xcd_barrier_complete(bar, b.x, nloc, nx); b.st[0] = nloc; b.st[1] = nx; }
;         const unsigned old = xb_add(&bar[XB_XSUB(b.x)], 1u);
;         const unsigned gen = old / nloc;
;         if (old + 1u == (gen + 1u) * nloc) {
;             __builtin_amdgcn_fence(__ATOMIC_RELEASE, "agent");
;             asm volatile("s_waitcnt vmcnt(0)" ::: "memory");
;             const unsigned og = xb_add(&bar[XB_TOP], 1u);
;             const unsigned tg = og / nx;
;             if (og + 1u == (tg + 1u) * nx) xb_add(&bar[XB_TOPGEN], 1u);
;             else XB_SPIN(xb_ld(&bar[XB_TOPGEN]) == tg, bar);
;             __builtin_amdgcn_fence(__ATOMIC_ACQUIRE, "agent");
;             xb_add(&bar[XB_XGEN(b.x)], 1u);
;             asm volatile("s_waitcnt vmcnt(0)" ::: "memory");
;         } else {
;             XB_SPIN(xb_ld(&bar[XB_XGEN(b.x)]) == gen, bar);
;             __builtin_amdgcn_fence(__ATOMIC_ACQUIRE, "agent");
;             asm volatile("s_waitcnt vmcnt(0)" ::: "memory");
;         }
.LBB0_61:
	s_lshl_b32 s4, s69, 8
	s_add_u32 s29, s33, s4
	s_addc_u32 s28, s68, 0
	v_mov_b32_e32 v1, s29
	v_add_co_u32_e32 v4, vcc, 0x1000, v1
	v_mov_b32_e32 v1, s28
	s_nop 0
	v_addc_co_u32_e32 v5, vcc, 0, v1, vcc
	v_mov_b32_e32 v1, 1
	flat_atomic_add v1, v[4:5], v1 offset:1024 sc0
	v_cvt_f32_u32_e32 v3, v2
	v_sub_u32_e32 v4, 0, v2
	v_rcp_iflag_f32_e32 v3, v3
	s_nop 0
	v_mul_f32_e32 v3, 0x4f7ffffe, v3
	v_cvt_u32_f32_e32 v3, v3
	v_mul_lo_u32 v4, v4, v3
	v_mul_hi_u32 v4, v3, v4
	v_add_u32_e32 v3, v3, v4
	s_waitcnt vmcnt(0) lgkmcnt(0)
	v_mul_hi_u32 v3, v1, v3
	v_mul_lo_u32 v5, v3, v2
	v_add_u32_e32 v4, 1, v1
	v_sub_u32_e32 v1, v1, v5
	v_add_u32_e32 v6, 1, v3
	v_cmp_ge_u32_e32 vcc, v1, v2
	v_sub_u32_e32 v5, v1, v2
	s_nop 0
	v_cndmask_b32_e32 v3, v3, v6, vcc
	v_cndmask_b32_e32 v1, v1, v5, vcc
	v_add_u32_e32 v5, 1, v3
	v_cmp_ge_u32_e32 vcc, v1, v2
	s_nop 1
	v_cndmask_b32_e32 v1, v3, v5, vcc
	v_mad_u64_u32 v[2:3], s[4:5], v2, v1, v[2:3]
	v_cmp_ne_u32_e32 vcc, v4, v2
	s_and_saveexec_b64 s[4:5], vcc
	s_xor_b64 s[4:5], exec, s[4:5]
	s_cbranch_execz .LBB0_74
	buffer_inv sc1
	s_add_u32 s10, s40, 0x83500
	s_addc_u32 s11, s41, 0
	v_mov_b64_e32 v[2:3], s[10:11]
	flat_load_dword v0, v[2:3] sc1
	s_waitcnt vmcnt(0) lgkmcnt(0)
	v_cmp_eq_u32_e32 vcc, v0, v1
	s_and_saveexec_b64 s[6:7], vcc
	s_cbranch_execz .LBB0_73
	s_add_u32 s8, s40, 0x80200
	s_addc_u32 s9, s41, 0
	s_mov_b32 s30, 1
	s_mov_b64 s[12:13], 0
	s_branch .LBB0_65

; __device__ __forceinline__ unsigned xb_ld(unsigned* p)              { return __hip_atomic_load(p, __ATOMIC_RELAXED, __HIP_MEMORY_SCOPE_AGENT); }
; __device__ __forceinline__ unsigned xb_add(unsigned* p, unsigned v) { return __hip_atomic_fetch_add(p, v, __ATOMIC_RELAXED, __HIP_MEMORY_SCOPE_AGENT); }
; #define XB_SPIN(cond, bar) do { unsigned _sp = 0; while (cond) { __builtin_amdgcn_s_sleep(1); \
;     if ((++_sp & 255u) == 0u) { if (xb_ld(&(bar)[XB_TMO])) break; if (_sp > XB_SPIN_CAP) { atomicAdd(&(bar)[XB_TMO], 1u); break; } } } } while (0)
; __device__ __forceinline__ void xcd_barrier(const XcdBarrier& b) {
;     ...
;     if (threadIdx.x == 0) {
;         unsigned* bar = b.bar;
;         __builtin_amdgcn_s_waitcnt(0);
;         unsigned nloc = b.st[0], nx = b.st[1];
;         if (nloc == 0u) { xcd_barrier_complete(bar, b.x, nloc, nx); b.st[0] = nloc; b.st[1] = nx; }
;         const unsigned old = xb_add(&bar[XB_XSUB(b.x)], 1u);
;         const unsigned gen = old / nloc;
;         if (old + 1u == (gen + 1u) * nloc) {
;             __builtin_amdgcn_fence(__ATOMIC_RELEASE, "agent");
;             asm volatile("s_waitcnt vmcnt(0)" ::: "memory");
;             const unsigned og = xb_add(&bar[XB_TOP], 1u);
;             const unsigned tg = og / nx;
;             if (og + 1u == (tg + 1u) * nx) xb_add(&bar[XB_TOPGEN], 1u);
;             else XB_SPIN(xb_ld(&bar[XB_TOPGEN]) == tg, bar);
;             __builtin_amdgcn_fence(__ATOMIC_ACQUIRE, "agent");
;             xb_add(&bar[XB_XGEN(b.x)], 1u);
;             asm volatile("s_waitcnt vmcnt(0)" ::: "memory");
;         } else {
;             XB_SPIN(xb_ld(&bar[XB_XGEN(b.x)]) == gen, bar);
.LBB0_495:
	s_lshl_b32 s3, s69, 8
	s_add_u32 s29, s33, s3
	s_addc_u32 s28, s68, 0
	v_mov_b32_e32 v1, s29
	v_add_co_u32_e32 v4, vcc, 0x1000, v1
	v_mov_b32_e32 v1, s28
	s_nop 0
	v_addc_co_u32_e32 v5, vcc, 0, v1, vcc
	v_mov_b32_e32 v1, 1
	flat_atomic_add v1, v[4:5], v1 offset:1024 sc0
	v_cvt_f32_u32_e32 v3, v2
	v_sub_u32_e32 v4, 0, v2
	v_rcp_iflag_f32_e32 v3, v3
	s_nop 0
	v_mul_f32_e32 v3, 0x4f7ffffe, v3
	v_cvt_u32_f32_e32 v3, v3
	v_mul_lo_u32 v4, v4, v3
	v_mul_hi_u32 v4, v3, v4
	v_add_u32_e32 v3, v3, v4
	s_waitcnt vmcnt(0) lgkmcnt(0)
	v_mul_hi_u32 v3, v1, v3
	v_mul_lo_u32 v5, v3, v2
	v_add_u32_e32 v4, 1, v1
	v_sub_u32_e32 v1, v1, v5
	v_add_u32_e32 v6, 1, v3
	v_cmp_ge_u32_e32 vcc, v1, v2
	v_sub_u32_e32 v5, v1, v2
	s_nop 0
	v_cndmask_b32_e32 v3, v3, v6, vcc
	v_cndmask_b32_e32 v1, v1, v5, vcc
	v_add_u32_e32 v5, 1, v3
	v_cmp_ge_u32_e32 vcc, v1, v2
	s_nop 1
	v_cndmask_b32_e32 v1, v3, v5, vcc
	v_mad_u64_u32 v[2:3], s[4:5], v2, v1, v[2:3]
	v_cmp_ne_u32_e32 vcc, v4, v2
	s_and_saveexec_b64 s[4:5], vcc
	s_xor_b64 s[4:5], exec, s[4:5]
	s_cbranch_execz .LBB0_508
	buffer_inv sc1
	s_add_u32 s10, s40, 0x83500
	s_addc_u32 s11, s41, 0
	v_mov_b64_e32 v[2:3], s[10:11]
	flat_load_dword v0, v[2:3] sc1
	s_waitcnt vmcnt(0) lgkmcnt(0)
	v_cmp_eq_u32_e32 vcc, v0, v1
	s_and_saveexec_b64 s[6:7], vcc
	s_cbranch_execz .LBB0_507
	s_add_u32 s8, s40, 0x80200
	s_addc_u32 s9, s41, 0
	s_mov_b32 s30, 1
	s_mov_b64 s[12:13], 0
	s_branch .LBB0_499

; __device__ __forceinline__ unsigned xb_ld(unsigned* p)              { return __hip_atomic_load(p, __ATOMIC_RELAXED, __HIP_MEMORY_SCOPE_AGENT); }
; __device__ __forceinline__ unsigned xb_add(unsigned* p, unsigned v) { return __hip_atomic_fetch_add(p, v, __ATOMIC_RELAXED, __HIP_MEMORY_SCOPE_AGENT); }
; #define XB_SPIN(cond, bar) do { unsigned _sp = 0; while (cond) { __builtin_amdgcn_s_sleep(1); \
;     if ((++_sp & 255u) == 0u) { if (xb_ld(&(bar)[XB_TMO])) break; if (_sp > XB_SPIN_CAP) { atomicAdd(&(bar)[XB_TMO], 1u); break; } } } } while (0)
; __device__ __forceinline__ void xcd_barrier(const XcdBarrier& b) {
;     ...
;     if (threadIdx.x == 0) {
;         unsigned* bar = b.bar;
;         __builtin_amdgcn_s_waitcnt(0);
;         unsigned nloc = b.st[0], nx = b.st[1];
;         if (nloc == 0u) { xcd_barrier_complete(bar, b.x, nloc, nx); b.st[0] = nloc; b.st[1] = nx; }
;         const unsigned old = xb_add(&bar[XB_XSUB(b.x)], 1u);
;         const unsigned gen = old / nloc;
;         if (old + 1u == (gen + 1u) * nloc) {
;             __builtin_amdgcn_fence(__ATOMIC_RELEASE, "agent");
;             asm volatile("s_waitcnt vmcnt(0)" ::: "memory");
;             const unsigned og = xb_add(&bar[XB_TOP], 1u);
;             const unsigned tg = og / nx;
;             if (og + 1u == (tg + 1u) * nx) xb_add(&bar[XB_TOPGEN], 1u);
;             else XB_SPIN(xb_ld(&bar[XB_TOPGEN]) == tg, bar);
;             __builtin_amdgcn_fence(__ATOMIC_ACQUIRE, "agent");
;             xb_add(&bar[XB_XGEN(b.x)], 1u);
;             asm volatile("s_waitcnt vmcnt(0)" ::: "memory");
;         } else {
;             XB_SPIN(xb_ld(&bar[XB_XGEN(b.x)]) == gen, bar);
.LBB0_779:
	s_lshl_b32 s2, s69, 8
	s_add_u32 s25, s33, s2
	s_addc_u32 s24, s68, 0
	v_mov_b32_e32 v1, s25
	v_add_co_u32_e32 v4, vcc, 0x1000, v1
	v_mov_b32_e32 v1, s24
	s_nop 0
	v_addc_co_u32_e32 v5, vcc, 0, v1, vcc
	v_mov_b32_e32 v1, 1
	flat_atomic_add v1, v[4:5], v1 offset:1024 sc0
	v_cvt_f32_u32_e32 v3, v2
	v_sub_u32_e32 v4, 0, v2
	v_rcp_iflag_f32_e32 v3, v3
	s_nop 0
	v_mul_f32_e32 v3, 0x4f7ffffe, v3
	v_cvt_u32_f32_e32 v3, v3
	v_mul_lo_u32 v4, v4, v3
	v_mul_hi_u32 v4, v3, v4
	v_add_u32_e32 v3, v3, v4
	s_waitcnt vmcnt(0) lgkmcnt(0)
	v_mul_hi_u32 v3, v1, v3
	v_mul_lo_u32 v5, v3, v2
	v_add_u32_e32 v4, 1, v1
	v_sub_u32_e32 v1, v1, v5
	v_add_u32_e32 v6, 1, v3
	v_cmp_ge_u32_e32 vcc, v1, v2
	v_sub_u32_e32 v5, v1, v2
	s_nop 0
	v_cndmask_b32_e32 v3, v3, v6, vcc
	v_cndmask_b32_e32 v1, v1, v5, vcc
	v_add_u32_e32 v5, 1, v3
	v_cmp_ge_u32_e32 vcc, v1, v2
	s_nop 1
	v_cndmask_b32_e32 v1, v3, v5, vcc
	v_mad_u64_u32 v[2:3], s[2:3], v2, v1, v[2:3]
	v_cmp_ne_u32_e32 vcc, v4, v2
	s_and_saveexec_b64 s[2:3], vcc
	s_xor_b64 s[2:3], exec, s[2:3]
	s_cbranch_execz .LBB0_792
	buffer_inv sc1
	s_add_u32 s8, s40, 0x83500
	s_addc_u32 s9, s41, 0
	v_mov_b64_e32 v[2:3], s[8:9]
	flat_load_dword v0, v[2:3] sc1
	s_waitcnt vmcnt(0) lgkmcnt(0)
	v_cmp_eq_u32_e32 vcc, v0, v1
	s_and_saveexec_b64 s[4:5], vcc
	s_cbranch_execz .LBB0_791
	s_add_u32 s6, s40, 0x80200
	s_addc_u32 s7, s41, 0
	s_mov_b32 s26, 1
	s_mov_b64 s[10:11], 0
	s_branch .LBB0_783
